# mix-phase weight-transpose items: 16 serialized HBM loads now issued together (both copies)
# speedup vs baseline: 1.0434x; 1.0148x over previous
.LBB0_641:
	s_or_b64 exec, exec, s[36:37]
	v_mov_b32_e32 v0, s1
	s_waitcnt lgkmcnt(0)
	s_barrier
	ds_read_b32 v0, v0
	s_mov_b64 s[36:37], -1
	s_waitcnt lgkmcnt(0)
	v_cmp_le_i32_e32 vcc, s15, v0
	v_readfirstlane_b32 s18, v0
	s_cbranch_vccnz .LBB0_636
	s_cmp_gt_i32 s18, 63
	s_cbranch_scc0 .LBB0_840
	s_lshl_b32 s42, s18, 1
	v_readlane_b32 s19, v251, 54
	s_add_i32 s19, s19, s42
	s_cmpk_gt_i32 s19, 0xff
	s_cbranch_scc0 .LBB0_775
	s_cmpk_gt_u32 s19, 0x1ff
	s_cbranch_scc0 .LBB0_751
	s_cmpk_gt_u32 s19, 0x3ff
	s_cbranch_scc0 .LBB0_704
	s_cmpk_gt_u32 s19, 0x4ff
	s_cbranch_scc0 .LBB0_696
	s_cmpk_gt_u32 s19, 0x5ff
	s_cbranch_scc0 .LBB0_673
	s_cmpk_gt_u32 s19, 0x6ff
	s_cbranch_scc0 .LBB0_654
	s_cmpk_gt_u32 s19, 0xa3f
	s_cbranch_scc0 .LBB0_651
	s_lshl_b32 s20, s19, 3
	s_and_b32 s20, s20, 0x7fffffc0
	s_add_i32 s70, s20, 0xffffae00
	s_lshl_b32 s20, s19, 8
	v_mov_b32_e32 v2, v189
	s_and_b32 s20, s20, 0x700
	s_lshl_b32 s21, s20, 2
	v_ashrrev_i32_e32 v3, 6, v2
	v_readlane_b32 s22, v252, 45
	v_add_u32_e32 v0, s70, v3
	s_add_u32 s22, s22, s21
	v_readlane_b32 s21, v252, 46
	v_lshlrev_b32_e32 v1, 4, v2
	s_addc_u32 s23, s21, 0
	v_and_b32_e32 v160, 0x3f0, v1
	v_ashrrev_i32_e32 v1, 31, v0
	v_lshl_add_u64 v[4:5], s[22:23], 0, v[160:161]
	v_lshlrev_b64 v[0:1], 13, v[0:1]
	v_lshl_add_u64 v[0:1], v[4:5], 0, v[0:1]
	global_load_dwordx4 v[24:27], v[0:1], off
	s_mov_b64 s[100:101], 0x8000
	v_lshl_add_u64 v[4:5], v[0:1], 0, s[100:101]
	global_load_dwordx4 v[28:31], v[4:5], off
	v_lshl_add_u64 v[4:5], v[4:5], 0, s[100:101]
	global_load_dwordx4 v[32:35], v[4:5], off
	v_lshl_add_u64 v[4:5], v[4:5], 0, s[100:101]
	global_load_dwordx4 v[36:39], v[4:5], off
	v_lshl_add_u64 v[4:5], v[4:5], 0, s[100:101]
	global_load_dwordx4 v[40:43], v[4:5], off
	v_lshl_add_u64 v[4:5], v[4:5], 0, s[100:101]
	global_load_dwordx4 v[44:47], v[4:5], off
	v_lshl_add_u64 v[4:5], v[4:5], 0, s[100:101]
	global_load_dwordx4 v[48:51], v[4:5], off
	v_lshl_add_u64 v[4:5], v[4:5], 0, s[100:101]
	global_load_dwordx4 v[52:55], v[4:5], off
	v_lshl_add_u64 v[4:5], v[4:5], 0, s[100:101]
	global_load_dwordx4 v[56:59], v[4:5], off
	v_lshl_add_u64 v[4:5], v[4:5], 0, s[100:101]
	global_load_dwordx4 v[60:63], v[4:5], off
	v_lshl_add_u64 v[4:5], v[4:5], 0, s[100:101]
	global_load_dwordx4 v[64:67], v[4:5], off
	v_lshl_add_u64 v[4:5], v[4:5], 0, s[100:101]
	global_load_dwordx4 v[68:71], v[4:5], off
	v_lshl_add_u64 v[4:5], v[4:5], 0, s[100:101]
	global_load_dwordx4 v[72:75], v[4:5], off
	v_lshl_add_u64 v[4:5], v[4:5], 0, s[100:101]
	global_load_dwordx4 v[76:79], v[4:5], off
	v_lshl_add_u64 v[4:5], v[4:5], 0, s[100:101]
	global_load_dwordx4 v[80:83], v[4:5], off
	v_lshl_add_u64 v[4:5], v[4:5], 0, s[100:101]
	global_load_dwordx4 v[84:87], v[4:5], off
	s_movk_i32 s36, 0x404
	v_mul_lo_u32 v3, v3, s36
	v_add3_u32 v3, s17, v160, v3
	s_lshl_b64 s[22:23], s[70:71], 1
	v_readlane_b32 s21, v252, 47
	s_nop 0
	s_add_u32 s22, s21, s22
	v_readlane_b32 s21, v252, 48
	s_nop 0
	s_addc_u32 s23, s21, s23
	s_waitcnt vmcnt(15)
	ds_write2_b32 v3, v24, v25 offset1:1
	ds_write2_b32 v3, v26, v27 offset0:2 offset1:3
	s_waitcnt vmcnt(14)
	v_add_u32_e32 v8, 0x1010, v3
	ds_write2_b32 v8, v28, v29 offset1:1
	ds_write2_b32 v8, v30, v31 offset0:2 offset1:3
	s_waitcnt vmcnt(13)
	v_add_u32_e32 v8, 0x2020, v3
	ds_write2_b32 v8, v32, v33 offset1:1
	ds_write2_b32 v8, v34, v35 offset0:2 offset1:3
	s_waitcnt vmcnt(12)
	v_add_u32_e32 v8, 0x3030, v3
	ds_write2_b32 v8, v36, v37 offset1:1
	ds_write2_b32 v8, v38, v39 offset0:2 offset1:3
	s_waitcnt vmcnt(11)
	v_add_u32_e32 v8, 0x4040, v3
	ds_write2_b32 v8, v40, v41 offset1:1
	ds_write2_b32 v8, v42, v43 offset0:2 offset1:3
	s_waitcnt vmcnt(10)
	v_add_u32_e32 v8, 0x5050, v3
	ds_write2_b32 v8, v44, v45 offset1:1
	ds_write2_b32 v8, v46, v47 offset0:2 offset1:3
	s_waitcnt vmcnt(9)
	v_add_u32_e32 v8, 0x6060, v3
	ds_write2_b32 v8, v48, v49 offset1:1
	ds_write2_b32 v8, v50, v51 offset0:2 offset1:3
	s_waitcnt vmcnt(8)
	v_add_u32_e32 v8, 0x7070, v3
	ds_write2_b32 v8, v52, v53 offset1:1
	ds_write2_b32 v8, v54, v55 offset0:2 offset1:3
	s_waitcnt vmcnt(7)
	v_add_u32_e32 v8, 0x8080, v3
	ds_write2_b32 v8, v56, v57 offset1:1
	ds_write2_b32 v8, v58, v59 offset0:2 offset1:3
	s_waitcnt vmcnt(6)
	v_add_u32_e32 v8, 0x9090, v3
	ds_write2_b32 v8, v60, v61 offset1:1
	ds_write2_b32 v8, v62, v63 offset0:2 offset1:3
	s_waitcnt vmcnt(5)
	v_add_u32_e32 v8, 0xa0a0, v3
	ds_write2_b32 v8, v64, v65 offset1:1
	ds_write2_b32 v8, v66, v67 offset0:2 offset1:3
	s_waitcnt vmcnt(4)
	v_add_u32_e32 v8, 0xb0b0, v3
	ds_write2_b32 v8, v68, v69 offset1:1
	ds_write2_b32 v8, v70, v71 offset0:2 offset1:3
	s_waitcnt vmcnt(3)
	v_add_u32_e32 v8, 0xc0c0, v3
	ds_write2_b32 v8, v72, v73 offset1:1
	ds_write2_b32 v8, v74, v75 offset0:2 offset1:3
	s_waitcnt vmcnt(2)
	v_add_u32_e32 v8, 0xd0d0, v3
	ds_write2_b32 v8, v76, v77 offset1:1
	ds_write2_b32 v8, v78, v79 offset0:2 offset1:3
	s_waitcnt vmcnt(1)
	v_add_u32_e32 v8, 0xe0e0, v3
	ds_write2_b32 v8, v80, v81 offset1:1
	ds_write2_b32 v8, v82, v83 offset0:2 offset1:3
	s_waitcnt vmcnt(0)
	v_add_u32_e32 v8, 0xf0f0, v3
	ds_write2_b32 v8, v84, v85 offset1:1
	ds_write2_b32 v8, v86, v87 offset0:2 offset1:3
	v_lshlrev_b32_e32 v0, 3, v2
	v_and_b32_e32 v3, 56, v0
	v_mov_b32_e32 v4, s17
	v_lshlrev_b32_e32 v160, 1, v3
	v_ashrrev_i32_e32 v8, 3, v2
	v_mad_u32_u24 v3, v3, s36, v4
	v_lshl_add_u32 v4, v8, 2, v3
	s_waitcnt lgkmcnt(0)
	s_barrier
	ds_read_b32 v5, v4
	ds_read_b32 v6, v4 offset:1028
	ds_read_b32 v7, v4 offset:2056
	ds_read_b32 v9, v4 offset:3084
	ds_read_b32 v10, v4 offset:4112
	ds_read_b32 v11, v4 offset:5140
	ds_read_b32 v12, v4 offset:6168
	ds_read_b32 v4, v4 offset:7196
	s_waitcnt lgkmcnt(4)
	v_bfe_u32 v20, v5, 16, 1
	v_add3_u32 v20, v5, v20, s94
	v_cvt_pk_bf16_f32 v9, v7, v9
	v_add_u32_e32 v8, s20, v8
	s_waitcnt lgkmcnt(0)
	v_bfe_u32 v19, v6, 16, 1
	v_mov_b32_e32 v5, v9
	v_ashrrev_i32_e32 v9, 31, v8
	v_lshl_add_u64 v[0:1], s[22:23], 0, v[160:161]
	v_add3_u32 v19, v6, v19, s94
	v_cvt_pk_bf16_f32 v10, v10, v11
	v_cvt_pk_bf16_f32 v4, v12, v4
	v_lshlrev_b64 v[8:9], 12, v[8:9]
	v_mov_b32_e32 v7, v4
	v_mov_b32_e32 v6, v10
	v_perm_b32 v4, v19, v20, s95
	v_lshl_add_u64 v[8:9], v[0:1], 0, v[8:9]
	global_store_dwordx4 v[8:9], v[4:7], off
	s_mov_b64 s[36:37], 0
	s_nop 0
	v_add_u32_e32 v4, 0x100, v2
	v_ashrrev_i32_e32 v8, 3, v4
	v_lshl_add_u32 v4, v8, 2, v3
	ds_read_b32 v5, v4
	ds_read_b32 v6, v4 offset:1028
	ds_read_b32 v7, v4 offset:2056
	ds_read_b32 v9, v4 offset:3084
	ds_read_b32 v10, v4 offset:4112
	ds_read_b32 v11, v4 offset:5140
	ds_read_b32 v12, v4 offset:6168
	ds_read_b32 v4, v4 offset:7196
	s_waitcnt lgkmcnt(4)
	v_bfe_u32 v20, v5, 16, 1
	v_add3_u32 v20, v5, v20, s94
	v_cvt_pk_bf16_f32 v9, v7, v9
	v_add_u32_e32 v8, s20, v8
	s_waitcnt lgkmcnt(0)
	v_bfe_u32 v19, v6, 16, 1
	v_mov_b32_e32 v5, v9
	v_ashrrev_i32_e32 v9, 31, v8
	v_add3_u32 v19, v6, v19, s94
	v_cvt_pk_bf16_f32 v10, v10, v11
	v_cvt_pk_bf16_f32 v4, v12, v4
	v_lshlrev_b64 v[8:9], 12, v[8:9]
	v_mov_b32_e32 v7, v4
	v_mov_b32_e32 v6, v10
	v_perm_b32 v4, v19, v20, s95
	v_lshl_add_u64 v[8:9], v[0:1], 0, v[8:9]
	global_store_dwordx4 v[8:9], v[4:7], off
	s_nop 1
	v_add_u32_e32 v4, 0x200, v2
	v_ashrrev_i32_e32 v8, 3, v4
	v_lshl_add_u32 v4, v8, 2, v3
	ds_read_b32 v5, v4
	ds_read_b32 v6, v4 offset:1028
	ds_read_b32 v7, v4 offset:2056
	ds_read_b32 v9, v4 offset:3084
	ds_read_b32 v10, v4 offset:4112
	ds_read_b32 v11, v4 offset:5140
	ds_read_b32 v12, v4 offset:6168
	ds_read_b32 v4, v4 offset:7196
	s_waitcnt lgkmcnt(4)
	v_bfe_u32 v20, v5, 16, 1
	v_add3_u32 v20, v5, v20, s94
	v_cvt_pk_bf16_f32 v9, v7, v9
	v_add_u32_e32 v8, s20, v8
	s_waitcnt lgkmcnt(0)
	v_bfe_u32 v19, v6, 16, 1
	v_mov_b32_e32 v5, v9
	v_ashrrev_i32_e32 v9, 31, v8
	v_add3_u32 v19, v6, v19, s94
	v_cvt_pk_bf16_f32 v10, v10, v11
	v_cvt_pk_bf16_f32 v4, v12, v4
	v_lshlrev_b64 v[8:9], 12, v[8:9]
	v_mov_b32_e32 v7, v4
	v_mov_b32_e32 v6, v10
	v_perm_b32 v4, v19, v20, s95
	v_lshl_add_u64 v[8:9], v[0:1], 0, v[8:9]
	global_store_dwordx4 v[8:9], v[4:7], off
	s_nop 1
	v_add_u32_e32 v4, 0x300, v2
	v_ashrrev_i32_e32 v8, 3, v4
	v_lshl_add_u32 v4, v8, 2, v3
	ds_read_b32 v5, v4
	ds_read_b32 v6, v4 offset:1028
	ds_read_b32 v7, v4 offset:2056
	ds_read_b32 v9, v4 offset:3084
	ds_read_b32 v10, v4 offset:4112
	ds_read_b32 v11, v4 offset:5140
	ds_read_b32 v12, v4 offset:6168
	ds_read_b32 v4, v4 offset:7196
	s_waitcnt lgkmcnt(4)
	v_bfe_u32 v20, v5, 16, 1
	v_add3_u32 v20, v5, v20, s94
	v_cvt_pk_bf16_f32 v9, v7, v9
	v_add_u32_e32 v8, s20, v8
	s_waitcnt lgkmcnt(0)
	v_bfe_u32 v19, v6, 16, 1
	v_mov_b32_e32 v5, v9
	v_ashrrev_i32_e32 v9, 31, v8
	v_add3_u32 v19, v6, v19, s94
	v_cvt_pk_bf16_f32 v10, v10, v11
	v_cvt_pk_bf16_f32 v4, v12, v4
	v_lshlrev_b64 v[8:9], 12, v[8:9]
	v_mov_b32_e32 v7, v4
	v_mov_b32_e32 v6, v10
	v_perm_b32 v4, v19, v20, s95
	v_lshl_add_u64 v[8:9], v[0:1], 0, v[8:9]
	global_store_dwordx4 v[8:9], v[4:7], off
	s_nop 1
	v_add_u32_e32 v4, 0x400, v2
	v_ashrrev_i32_e32 v8, 3, v4
	v_lshl_add_u32 v4, v8, 2, v3
	ds_read_b32 v5, v4
	ds_read_b32 v6, v4 offset:1028
	ds_read_b32 v7, v4 offset:2056
	ds_read_b32 v9, v4 offset:3084
	ds_read_b32 v10, v4 offset:4112
	ds_read_b32 v11, v4 offset:5140
	ds_read_b32 v12, v4 offset:6168
	ds_read_b32 v4, v4 offset:7196
	s_waitcnt lgkmcnt(4)
	v_bfe_u32 v20, v5, 16, 1
	v_add3_u32 v20, v5, v20, s94
	v_cvt_pk_bf16_f32 v9, v7, v9
	v_add_u32_e32 v8, s20, v8
	s_waitcnt lgkmcnt(0)
	v_bfe_u32 v19, v6, 16, 1
	v_mov_b32_e32 v5, v9
	v_ashrrev_i32_e32 v9, 31, v8
	v_add3_u32 v19, v6, v19, s94
	v_cvt_pk_bf16_f32 v10, v10, v11
	v_cvt_pk_bf16_f32 v4, v12, v4
	v_lshlrev_b64 v[8:9], 12, v[8:9]
	v_mov_b32_e32 v7, v4
	v_mov_b32_e32 v6, v10
	v_perm_b32 v4, v19, v20, s95
	v_lshl_add_u64 v[8:9], v[0:1], 0, v[8:9]
	global_store_dwordx4 v[8:9], v[4:7], off
	s_nop 1
	v_add_u32_e32 v4, 0x500, v2
	v_ashrrev_i32_e32 v8, 3, v4
	v_lshl_add_u32 v4, v8, 2, v3
	ds_read_b32 v5, v4
	ds_read_b32 v6, v4 offset:1028
	ds_read_b32 v7, v4 offset:2056
	ds_read_b32 v9, v4 offset:3084
	ds_read_b32 v10, v4 offset:4112
	ds_read_b32 v11, v4 offset:5140
	ds_read_b32 v12, v4 offset:6168
	ds_read_b32 v4, v4 offset:7196
	s_waitcnt lgkmcnt(4)
	v_bfe_u32 v20, v5, 16, 1
	v_add3_u32 v20, v5, v20, s94
	v_cvt_pk_bf16_f32 v9, v7, v9
	v_add_u32_e32 v8, s20, v8
	s_waitcnt lgkmcnt(0)
	v_bfe_u32 v19, v6, 16, 1
	v_mov_b32_e32 v5, v9
	v_ashrrev_i32_e32 v9, 31, v8
	v_add3_u32 v19, v6, v19, s94
	v_cvt_pk_bf16_f32 v10, v10, v11
	v_cvt_pk_bf16_f32 v4, v12, v4
	v_lshlrev_b64 v[8:9], 12, v[8:9]
	v_mov_b32_e32 v7, v4
	v_mov_b32_e32 v6, v10
	v_perm_b32 v4, v19, v20, s95
	v_lshl_add_u64 v[8:9], v[0:1], 0, v[8:9]
	global_store_dwordx4 v[8:9], v[4:7], off
	s_nop 1
	v_add_u32_e32 v4, 0x600, v2
	v_ashrrev_i32_e32 v8, 3, v4
	v_lshl_add_u32 v4, v8, 2, v3
	ds_read_b32 v5, v4
	ds_read_b32 v6, v4 offset:1028
	ds_read_b32 v7, v4 offset:2056
	ds_read_b32 v9, v4 offset:3084
	ds_read_b32 v10, v4 offset:4112
	ds_read_b32 v11, v4 offset:5140
	ds_read_b32 v12, v4 offset:6168
	ds_read_b32 v4, v4 offset:7196
	s_waitcnt lgkmcnt(4)
	v_bfe_u32 v20, v5, 16, 1
	v_add3_u32 v20, v5, v20, s94
	v_cvt_pk_bf16_f32 v9, v7, v9
	v_add_u32_e32 v8, s20, v8
	s_waitcnt lgkmcnt(0)
	v_bfe_u32 v19, v6, 16, 1
	v_mov_b32_e32 v5, v9
	v_ashrrev_i32_e32 v9, 31, v8
	v_add3_u32 v19, v6, v19, s94
	v_cvt_pk_bf16_f32 v10, v10, v11
	v_cvt_pk_bf16_f32 v4, v12, v4
	v_lshlrev_b64 v[8:9], 12, v[8:9]
	v_mov_b32_e32 v7, v4
	v_mov_b32_e32 v6, v10
	v_perm_b32 v4, v19, v20, s95
	v_lshl_add_u64 v[8:9], v[0:1], 0, v[8:9]
	v_add_u32_e32 v2, 0x700, v2
	global_store_dwordx4 v[8:9], v[4:7], off
	s_nop 1
	v_ashrrev_i32_e32 v6, 3, v2
	v_lshl_add_u32 v2, v6, 2, v3
	ds_read_b32 v3, v2
	ds_read_b32 v4, v2 offset:1028
	ds_read_b32 v5, v2 offset:2056
	ds_read_b32 v7, v2 offset:3084
	ds_read_b32 v8, v2 offset:4112
	ds_read_b32 v9, v2 offset:5140
	ds_read_b32 v10, v2 offset:6168
	ds_read_b32 v2, v2 offset:7196
	s_waitcnt lgkmcnt(4)
	v_bfe_u32 v18, v3, 16, 1
	v_add3_u32 v18, v3, v18, s94
	v_cvt_pk_bf16_f32 v7, v5, v7
	v_add_u32_e32 v6, s20, v6
	s_waitcnt lgkmcnt(0)
	v_bfe_u32 v17, v4, 16, 1
	v_mov_b32_e32 v3, v7
	v_ashrrev_i32_e32 v7, 31, v6
	v_add3_u32 v17, v4, v17, s94
	v_cvt_pk_bf16_f32 v8, v8, v9
	v_cvt_pk_bf16_f32 v2, v10, v2
	v_lshlrev_b64 v[6:7], 12, v[6:7]
	v_mov_b32_e32 v5, v2
	v_mov_b32_e32 v4, v8
	v_perm_b32 v2, v17, v18, s95
	v_lshl_add_u64 v[0:1], v[0:1], 0, v[6:7]
	global_store_dwordx4 v[0:1], v[2:5], off
	s_barrier
.LBB0_651:
	s_andn2_b64 vcc, exec, s[36:37]
	s_cbranch_vccnz .LBB0_653
	s_add_i32 s20, s19, 0xf900
	s_and_b32 s21, s20, 0xffff
	s_mulk_i32 s21, 0x4ec5
	s_lshr_b32 s21, s21, 19
	s_mul_i32 s22, s21, 26
	s_sub_i32 s20, s20, s22
	s_lshl_b32 s20, s20, 8
	s_and_b32 s20, s20, 0xff00
	v_mov_b32_e32 v22, v189
	s_lshl_b32 s22, s20, 2
	v_readlane_b32 s23, v252, 49
	s_add_u32 s22, s23, s22
	v_ashrrev_i32_e32 v23, 6, v22
	v_readlane_b32 s23, v252, 50
	v_lshlrev_b32_e32 v0, 4, v22
	v_lshl_add_u32 v26, s21, 6, v23
	s_addc_u32 s23, s23, 0
	v_and_b32_e32 v160, 0x3f0, v0
	v_lshl_add_u64 v[0:1], s[22:23], 0, v[160:161]
	s_movk_i32 s36, 0x6800
	v_add_u32_e32 v2, 4, v26
	v_mad_i64_i32 v[28:29], s[22:23], v2, s36, v[0:1]
	v_add_u32_e32 v2, 8, v26
	v_mad_i64_i32 v[30:31], s[22:23], v2, s36, v[0:1]
	v_add_u32_e32 v2, 12, v26
	v_mad_i64_i32 v[32:33], s[22:23], v2, s36, v[0:1]
	v_add_u32_e32 v2, 16, v26
	v_mad_i64_i32 v[34:35], s[22:23], v2, s36, v[0:1]
	v_add_u32_e32 v2, 20, v26
	v_mad_i64_i32 v[20:21], s[22:23], v2, s36, v[0:1]
	v_add_u32_e32 v2, 24, v26
	v_mad_i64_i32 v[18:19], s[22:23], v2, s36, v[0:1]
	v_add_u32_e32 v2, 28, v26
	v_mad_i64_i32 v[16:17], s[22:23], v2, s36, v[0:1]
	v_add_u32_e32 v2, 32, v26
	v_mad_i64_i32 v[14:15], s[22:23], v2, s36, v[0:1]
	v_add_u32_e32 v2, 36, v26
	v_mad_i64_i32 v[12:13], s[22:23], v2, s36, v[0:1]
	v_add_u32_e32 v2, 40, v26
	v_mad_i64_i32 v[10:11], s[22:23], v2, s36, v[0:1]
	v_add_u32_e32 v2, 44, v26
	v_mad_i64_i32 v[8:9], s[22:23], v2, s36, v[0:1]
	v_add_u32_e32 v2, 48, v26
	v_mad_i64_i32 v[6:7], s[22:23], v2, s36, v[0:1]
	v_add_u32_e32 v2, 52, v26
	v_mad_i64_i32 v[24:25], s[22:23], v26, s36, v[0:1]
	v_mad_i64_i32 v[4:5], s[22:23], v2, s36, v[0:1]
	v_add_u32_e32 v2, 56, v26
	v_add_u32_e32 v26, 60, v26
	v_mad_i64_i32 v[2:3], s[22:23], v2, s36, v[0:1]
	v_mad_i64_i32 v[0:1], s[22:23], v26, s36, v[0:1]
	global_load_dwordx4 v[24:27], v[24:25], off
	s_movk_i32 s36, 0x404
	v_mul_lo_u32 v23, v23, s36
	v_add3_u32 v23, s17, v160, v23
	v_add_u32_e32 v36, 0x1010, v23
	s_lshl_b32 s21, s21, 7
	v_readlane_b32 s22, v252, 51
	s_add_u32 s22, s22, s21
	v_readlane_b32 s21, v252, 52
	s_addc_u32 s23, s21, 0
	global_load_dwordx4 v[40:43], v[28:29], off
	global_load_dwordx4 v[44:47], v[30:31], off
	global_load_dwordx4 v[48:51], v[32:33], off
	global_load_dwordx4 v[52:55], v[34:35], off
	global_load_dwordx4 v[56:59], v[20:21], off
	global_load_dwordx4 v[60:63], v[18:19], off
	global_load_dwordx4 v[64:67], v[16:17], off
	global_load_dwordx4 v[68:71], v[14:15], off
	global_load_dwordx4 v[72:75], v[12:13], off
	global_load_dwordx4 v[76:79], v[10:11], off
	global_load_dwordx4 v[80:83], v[8:9], off
	global_load_dwordx4 v[84:87], v[6:7], off
	global_load_dwordx4 v[88:91], v[4:5], off
	global_load_dwordx4 v[92:95], v[2:3], off
	global_load_dwordx4 v[96:99], v[0:1], off
	s_waitcnt vmcnt(15)
	ds_write2_b32 v23, v24, v25 offset1:1
	ds_write2_b32 v23, v26, v27 offset0:2 offset1:3
	s_nop 0
	v_add_u32_e32 v28, 0x2020, v23
	s_waitcnt vmcnt(14)
	ds_write2_b32 v36, v40, v41 offset1:1
	v_add_u32_e32 v24, 0x1018, v23
	ds_write2_b32 v24, v42, v43 offset1:1
	s_nop 0
	s_waitcnt vmcnt(13)
	ds_write2_b32 v28, v44, v45 offset1:1
	v_add_u32_e32 v24, 0x2028, v23
	ds_write2_b32 v24, v46, v47 offset1:1
	s_nop 0
	v_add_u32_e32 v28, 0x3030, v23
	s_waitcnt vmcnt(12)
	ds_write2_b32 v28, v48, v49 offset1:1
	v_add_u32_e32 v24, 0x3038, v23
	ds_write2_b32 v24, v50, v51 offset1:1
	s_nop 0
	v_add_u32_e32 v28, 0x4040, v23
	s_waitcnt vmcnt(11)
	ds_write2_b32 v28, v52, v53 offset1:1
	v_add_u32_e32 v24, 0x4048, v23
	ds_write2_b32 v24, v54, v55 offset1:1
	s_nop 0
	v_add_u32_e32 v20, 0x5058, v23
	v_add_u32_e32 v28, 0x5050, v23
	s_waitcnt vmcnt(10)
	ds_write2_b32 v20, v58, v59 offset1:1
	s_nop 0
	ds_write2_b32 v28, v56, v57 offset1:1
	v_add_u32_e32 v24, 0x6060, v23
	s_waitcnt vmcnt(9)
	ds_write2_b32 v24, v60, v61 offset1:1
	v_add_u32_e32 v18, 0x6068, v23
	ds_write2_b32 v18, v62, v63 offset1:1
	s_nop 0
	v_add_u32_e32 v20, 0x7070, v23
	s_waitcnt vmcnt(8)
	ds_write2_b32 v20, v64, v65 offset1:1
	v_add_u32_e32 v16, 0x7078, v23
	ds_write2_b32 v16, v66, v67 offset1:1
	s_nop 0
	v_add_u32_e32 v18, 0x8080, v23
	s_waitcnt vmcnt(7)
	ds_write2_b32 v18, v68, v69 offset1:1
	v_add_u32_e32 v14, 0x8088, v23
	ds_write2_b32 v14, v70, v71 offset1:1
	s_nop 0
	v_add_u32_e32 v16, 0x9090, v23
	s_waitcnt vmcnt(6)
	ds_write2_b32 v16, v72, v73 offset1:1
	v_add_u32_e32 v12, 0x9098, v23
	ds_write2_b32 v12, v74, v75 offset1:1
	s_nop 0
	v_add_u32_e32 v14, 0xa0a0, v23
	s_waitcnt vmcnt(5)
	ds_write2_b32 v14, v76, v77 offset1:1
	v_add_u32_e32 v10, 0xa0a8, v23
	ds_write2_b32 v10, v78, v79 offset1:1
	s_nop 0
	v_add_u32_e32 v12, 0xb0b0, v23
	s_waitcnt vmcnt(4)
	ds_write2_b32 v12, v80, v81 offset1:1
	v_add_u32_e32 v8, 0xb0b8, v23
	ds_write2_b32 v8, v82, v83 offset1:1
	s_nop 0
	v_add_u32_e32 v10, 0xc0c0, v23
	s_waitcnt vmcnt(3)
	ds_write2_b32 v10, v84, v85 offset1:1
	v_add_u32_e32 v6, 0xc0c8, v23
	ds_write2_b32 v6, v86, v87 offset1:1
	s_nop 0
	v_add_u32_e32 v8, 0xd0d0, v23
	s_waitcnt vmcnt(2)
	ds_write2_b32 v8, v88, v89 offset1:1
	v_add_u32_e32 v4, 0xd0d8, v23
	ds_write2_b32 v4, v90, v91 offset1:1
	s_nop 0
	v_add_u32_e32 v6, 0xe0e0, v23
	s_waitcnt vmcnt(1)
	ds_write2_b32 v6, v92, v93 offset1:1
	v_add_u32_e32 v2, 0xe0e8, v23
	ds_write2_b32 v2, v94, v95 offset1:1
	s_nop 0
	v_add_u32_e32 v4, 0xf0f0, v23
	s_waitcnt vmcnt(0)
	ds_write2_b32 v4, v96, v97 offset1:1
	v_add_u32_e32 v0, 0xf0f8, v23
	ds_write2_b32 v0, v98, v99 offset1:1
	v_lshlrev_b32_e32 v0, 3, v22
	v_and_b32_e32 v2, 56, v0
	v_mov_b32_e32 v4, s17
	v_lshlrev_b32_e32 v160, 1, v2
	v_ashrrev_i32_e32 v3, 3, v22
	v_mad_u32_u24 v2, v2, s36, v4
	v_lshl_add_u32 v4, v3, 2, v2
	s_waitcnt lgkmcnt(0)
	v_mov_b32_e32 v1, v97
	v_mov_b32_e32 v5, v95
	v_mov_b32_e32 v7, v91
	v_mov_b32_e32 v9, v87
	v_mov_b32_e32 v11, v83
	v_mov_b32_e32 v13, v79
	v_mov_b32_e32 v15, v75
	v_mov_b32_e32 v17, v71
	v_mov_b32_e32 v19, v67
	v_mov_b32_e32 v21, v63
	v_mov_b32_e32 v25, v57
	v_mov_b32_e32 v26, v58
	v_mov_b32_e32 v27, v59
	s_barrier
	ds_read_b32 v5, v4
	ds_read_b32 v6, v4 offset:1028
	ds_read_b32 v7, v4 offset:2056
	ds_read_b32 v8, v4 offset:3084
	ds_read_b32 v9, v4 offset:4112
	ds_read_b32 v10, v4 offset:5140
	ds_read_b32 v11, v4 offset:6168
	ds_read_b32 v4, v4 offset:7196
	s_waitcnt lgkmcnt(4)
	v_bfe_u32 v19, v5, 16, 1
	s_waitcnt lgkmcnt(2)
	v_bfe_u32 v18, v6, 16, 1
	v_add3_u32 v19, v5, v19, s94
	v_cvt_pk_bf16_f32 v8, v7, v8
	v_add3_u32 v18, v6, v18, s94
	v_cvt_pk_bf16_f32 v9, v9, v10
	v_mov_b32_e32 v5, v8
	v_add_u32_e32 v8, s20, v3
	s_waitcnt lgkmcnt(0)
	v_mov_b32_e32 v6, v9
	v_ashrrev_i32_e32 v9, 31, v8
	v_lshl_add_u64 v[0:1], s[22:23], 0, v[160:161]
	v_cvt_pk_bf16_f32 v4, v11, v4
	v_lshlrev_b64 v[8:9], 12, v[8:9]
	v_add_u32_e32 v3, 0x100, v22
	v_mov_b32_e32 v7, v4
	v_perm_b32 v4, v18, v19, s95
	v_lshl_add_u64 v[8:9], v[0:1], 0, v[8:9]
	v_ashrrev_i32_e32 v3, 3, v3
	global_store_dwordx4 v[8:9], v[4:7], off
	s_nop 1
	v_lshl_add_u32 v4, v3, 2, v2
	ds_read_b32 v5, v4
	ds_read_b32 v6, v4 offset:1028
	ds_read_b32 v7, v4 offset:2056
	ds_read_b32 v8, v4 offset:3084
	ds_read_b32 v9, v4 offset:4112
	ds_read_b32 v10, v4 offset:5140
	ds_read_b32 v11, v4 offset:6168
	ds_read_b32 v4, v4 offset:7196
	s_waitcnt lgkmcnt(4)
	v_bfe_u32 v19, v5, 16, 1
	s_waitcnt lgkmcnt(2)
	v_bfe_u32 v18, v6, 16, 1
	v_add3_u32 v19, v5, v19, s94
	v_cvt_pk_bf16_f32 v8, v7, v8
	v_add3_u32 v18, v6, v18, s94
	v_cvt_pk_bf16_f32 v9, v9, v10
	v_mov_b32_e32 v5, v8
	v_add_u32_e32 v8, s20, v3
	s_waitcnt lgkmcnt(0)
	v_mov_b32_e32 v6, v9
	v_ashrrev_i32_e32 v9, 31, v8
	v_cvt_pk_bf16_f32 v4, v11, v4
	v_lshlrev_b64 v[8:9], 12, v[8:9]
	v_add_u32_e32 v3, 0x200, v22
	v_mov_b32_e32 v7, v4
	v_perm_b32 v4, v18, v19, s95
	v_lshl_add_u64 v[8:9], v[0:1], 0, v[8:9]
	v_ashrrev_i32_e32 v3, 3, v3
	global_store_dwordx4 v[8:9], v[4:7], off
	s_nop 1
	v_lshl_add_u32 v4, v3, 2, v2
	ds_read_b32 v5, v4
	ds_read_b32 v6, v4 offset:1028
	ds_read_b32 v7, v4 offset:2056
	ds_read_b32 v8, v4 offset:3084
	ds_read_b32 v9, v4 offset:4112
	ds_read_b32 v10, v4 offset:5140
	ds_read_b32 v11, v4 offset:6168
	ds_read_b32 v4, v4 offset:7196
	s_waitcnt lgkmcnt(4)
	v_bfe_u32 v19, v5, 16, 1
	s_waitcnt lgkmcnt(2)
	v_bfe_u32 v18, v6, 16, 1
	v_add3_u32 v19, v5, v19, s94
	v_cvt_pk_bf16_f32 v8, v7, v8
	v_add3_u32 v18, v6, v18, s94
	v_cvt_pk_bf16_f32 v9, v9, v10
	v_mov_b32_e32 v5, v8
	v_add_u32_e32 v8, s20, v3
	s_waitcnt lgkmcnt(0)
	v_mov_b32_e32 v6, v9
	v_ashrrev_i32_e32 v9, 31, v8
	v_cvt_pk_bf16_f32 v4, v11, v4
	v_lshlrev_b64 v[8:9], 12, v[8:9]
	v_add_u32_e32 v3, 0x300, v22
	v_mov_b32_e32 v7, v4
	v_perm_b32 v4, v18, v19, s95
	v_lshl_add_u64 v[8:9], v[0:1], 0, v[8:9]
	v_ashrrev_i32_e32 v3, 3, v3
	global_store_dwordx4 v[8:9], v[4:7], off
	s_nop 1
	v_lshl_add_u32 v4, v3, 2, v2
	ds_read_b32 v5, v4
	ds_read_b32 v6, v4 offset:1028
	ds_read_b32 v7, v4 offset:2056
	ds_read_b32 v8, v4 offset:3084
	ds_read_b32 v9, v4 offset:4112
	ds_read_b32 v10, v4 offset:5140
	ds_read_b32 v11, v4 offset:6168
	ds_read_b32 v4, v4 offset:7196
	s_waitcnt lgkmcnt(4)
	v_bfe_u32 v19, v5, 16, 1
	s_waitcnt lgkmcnt(2)
	v_bfe_u32 v18, v6, 16, 1
	v_add3_u32 v19, v5, v19, s94
	v_cvt_pk_bf16_f32 v8, v7, v8
	v_add3_u32 v18, v6, v18, s94
	v_cvt_pk_bf16_f32 v9, v9, v10
	v_mov_b32_e32 v5, v8
	v_add_u32_e32 v8, s20, v3
	s_waitcnt lgkmcnt(0)
	v_mov_b32_e32 v6, v9
	v_ashrrev_i32_e32 v9, 31, v8
	v_cvt_pk_bf16_f32 v4, v11, v4
	v_lshlrev_b64 v[8:9], 12, v[8:9]
	v_add_u32_e32 v3, 0x400, v22
	v_mov_b32_e32 v7, v4
	v_perm_b32 v4, v18, v19, s95
	v_lshl_add_u64 v[8:9], v[0:1], 0, v[8:9]
	v_ashrrev_i32_e32 v3, 3, v3
	global_store_dwordx4 v[8:9], v[4:7], off
	s_nop 1
	v_lshl_add_u32 v4, v3, 2, v2
	ds_read_b32 v5, v4
	ds_read_b32 v6, v4 offset:1028
	ds_read_b32 v7, v4 offset:2056
	ds_read_b32 v8, v4 offset:3084
	ds_read_b32 v9, v4 offset:4112
	ds_read_b32 v10, v4 offset:5140
	ds_read_b32 v11, v4 offset:6168
	ds_read_b32 v4, v4 offset:7196
	s_waitcnt lgkmcnt(4)
	v_bfe_u32 v19, v5, 16, 1
	s_waitcnt lgkmcnt(2)
	v_bfe_u32 v18, v6, 16, 1
	v_add3_u32 v19, v5, v19, s94
	v_cvt_pk_bf16_f32 v8, v7, v8
	v_add3_u32 v18, v6, v18, s94
	v_cvt_pk_bf16_f32 v9, v9, v10
	v_mov_b32_e32 v5, v8
	v_add_u32_e32 v8, s20, v3
	s_waitcnt lgkmcnt(0)
	v_mov_b32_e32 v6, v9
	v_ashrrev_i32_e32 v9, 31, v8
	v_cvt_pk_bf16_f32 v4, v11, v4
	v_lshlrev_b64 v[8:9], 12, v[8:9]
	v_add_u32_e32 v3, 0x500, v22
	v_mov_b32_e32 v7, v4
	v_perm_b32 v4, v18, v19, s95
	v_lshl_add_u64 v[8:9], v[0:1], 0, v[8:9]
	v_ashrrev_i32_e32 v3, 3, v3
	global_store_dwordx4 v[8:9], v[4:7], off
	s_nop 1
	v_lshl_add_u32 v4, v3, 2, v2
	ds_read_b32 v5, v4
	ds_read_b32 v6, v4 offset:1028
	ds_read_b32 v7, v4 offset:2056
	ds_read_b32 v8, v4 offset:3084
	ds_read_b32 v9, v4 offset:4112
	ds_read_b32 v10, v4 offset:5140
	ds_read_b32 v11, v4 offset:6168
	ds_read_b32 v4, v4 offset:7196
	s_waitcnt lgkmcnt(4)
	v_bfe_u32 v19, v5, 16, 1
	s_waitcnt lgkmcnt(2)
	v_bfe_u32 v18, v6, 16, 1
	v_add3_u32 v19, v5, v19, s94
	v_cvt_pk_bf16_f32 v8, v7, v8
	v_add3_u32 v18, v6, v18, s94
	v_cvt_pk_bf16_f32 v9, v9, v10
	v_mov_b32_e32 v5, v8
	v_add_u32_e32 v8, s20, v3
	s_waitcnt lgkmcnt(0)
	v_mov_b32_e32 v6, v9
	v_ashrrev_i32_e32 v9, 31, v8
	v_cvt_pk_bf16_f32 v4, v11, v4
	v_lshlrev_b64 v[8:9], 12, v[8:9]
	v_add_u32_e32 v3, 0x600, v22
	v_mov_b32_e32 v7, v4
	v_perm_b32 v4, v18, v19, s95
	v_lshl_add_u64 v[8:9], v[0:1], 0, v[8:9]
	v_ashrrev_i32_e32 v3, 3, v3
	global_store_dwordx4 v[8:9], v[4:7], off
	s_nop 1
	v_lshl_add_u32 v4, v3, 2, v2
	ds_read_b32 v5, v4
	ds_read_b32 v6, v4 offset:1028
	ds_read_b32 v7, v4 offset:2056
	ds_read_b32 v8, v4 offset:3084
	ds_read_b32 v9, v4 offset:4112
	ds_read_b32 v10, v4 offset:5140
	ds_read_b32 v11, v4 offset:6168
	ds_read_b32 v4, v4 offset:7196
	s_waitcnt lgkmcnt(4)
	v_bfe_u32 v19, v5, 16, 1
	s_waitcnt lgkmcnt(2)
	v_bfe_u32 v18, v6, 16, 1
	v_add3_u32 v19, v5, v19, s94
	v_cvt_pk_bf16_f32 v8, v7, v8
	v_add3_u32 v18, v6, v18, s94
	v_cvt_pk_bf16_f32 v9, v9, v10
	v_mov_b32_e32 v5, v8
	v_add_u32_e32 v8, s20, v3
	s_waitcnt lgkmcnt(0)
	v_mov_b32_e32 v6, v9
	v_ashrrev_i32_e32 v9, 31, v8
	v_cvt_pk_bf16_f32 v4, v11, v4
	v_lshlrev_b64 v[8:9], 12, v[8:9]
	v_mov_b32_e32 v7, v4
	v_perm_b32 v4, v18, v19, s95
	v_lshl_add_u64 v[8:9], v[0:1], 0, v[8:9]
	v_add_u32_e32 v3, 0x700, v22
	global_store_dwordx4 v[8:9], v[4:7], off
	s_nop 1
	v_ashrrev_i32_e32 v6, 3, v3
	v_lshl_add_u32 v2, v6, 2, v2
	ds_read_b32 v3, v2
	ds_read_b32 v4, v2 offset:1028
	ds_read_b32 v5, v2 offset:2056
	ds_read_b32 v7, v2 offset:3084
	ds_read_b32 v8, v2 offset:4112
	ds_read_b32 v9, v2 offset:5140
	ds_read_b32 v10, v2 offset:6168
	ds_read_b32 v2, v2 offset:7196
	s_waitcnt lgkmcnt(4)
	v_bfe_u32 v18, v3, 16, 1
	v_add3_u32 v18, v3, v18, s94
	v_cvt_pk_bf16_f32 v7, v5, v7
	v_add_u32_e32 v6, s20, v6
	s_waitcnt lgkmcnt(0)
	v_bfe_u32 v11, v2, 16, 1
	v_bfe_u32 v12, v10, 16, 1
	v_bfe_u32 v13, v9, 16, 1
	v_bfe_u32 v14, v8, 16, 1
	v_bfe_u32 v17, v4, 16, 1
	v_mov_b32_e32 v3, v7
	v_ashrrev_i32_e32 v7, 31, v6
	v_add3_u32 v17, v4, v17, s94
	v_add3_u32 v4, v8, v14, s94
	v_add3_u32 v8, v9, v13, s94
	v_add3_u32 v5, v10, v12, s94
	v_add3_u32 v2, v2, v11, s94
	v_lshlrev_b64 v[6:7], 12, v[6:7]
	v_perm_b32 v5, v2, v5, s95
	v_perm_b32 v4, v8, v4, s95
	v_perm_b32 v2, v17, v18, s95
	v_lshl_add_u64 v[0:1], v[0:1], 0, v[6:7]
	global_store_dwordx4 v[0:1], v[2:5], off
	s_barrier

	.amdhsa_kernel _Z11mega_kernel6Params
		.amdhsa_group_segment_fixed_size 0
		.amdhsa_private_segment_fixed_size 0
		.amdhsa_kernarg_size 496
		.amdhsa_user_sgpr_count 2
		.amdhsa_user_sgpr_dispatch_ptr 0
		.amdhsa_user_sgpr_queue_ptr 0
		.amdhsa_user_sgpr_kernarg_segment_ptr 1
		.amdhsa_user_sgpr_dispatch_id 0
		.amdhsa_user_sgpr_kernarg_preload_length 0
		.amdhsa_user_sgpr_kernarg_preload_offset 0
		.amdhsa_user_sgpr_private_segment_size 0
		.amdhsa_uses_dynamic_stack 0
		.amdhsa_enable_private_segment 0
		.amdhsa_system_sgpr_workgroup_id_x 1
		.amdhsa_system_sgpr_workgroup_id_y 0
		.amdhsa_system_sgpr_workgroup_id_z 0
		.amdhsa_system_sgpr_workgroup_info 0
		.amdhsa_system_vgpr_workitem_id 2
		.amdhsa_next_free_vgpr 254
		.amdhsa_next_free_sgpr 102
		.amdhsa_accum_offset 256
		.amdhsa_reserve_vcc 1
		.amdhsa_float_round_mode_32 0
		.amdhsa_float_round_mode_16_64 0
		.amdhsa_float_denorm_mode_32 3
		.amdhsa_float_denorm_mode_16_64 3
		.amdhsa_dx10_clamp 1
		.amdhsa_ieee_mode 1
		.amdhsa_fp16_overflow 0
		.amdhsa_tg_split 0
		.amdhsa_exception_fp_ieee_invalid_op 0
		.amdhsa_exception_fp_denorm_src 0
		.amdhsa_exception_fp_ieee_div_zero 0
		.amdhsa_exception_fp_ieee_overflow 0
		.amdhsa_exception_fp_ieee_underflow 0
		.amdhsa_exception_fp_ieee_inexact 0
		.amdhsa_exception_int_div_zero 0
	.end_amdhsa_kernel

amdhsa.kernels:
  - .agpr_count:     0
    .args:
      - .offset:         0
        .size:           240
        .value_kind:     by_value
      - .offset:         240
        .size:           4
        .value_kind:     hidden_block_count_x
      - .offset:         244
        .size:           4
        .value_kind:     hidden_block_count_y
      - .offset:         248
        .size:           4
        .value_kind:     hidden_block_count_z
      - .offset:         252
        .size:           2
        .value_kind:     hidden_group_size_x
      - .offset:         254
        .size:           2
        .value_kind:     hidden_group_size_y
      - .offset:         256
        .size:           2
        .value_kind:     hidden_group_size_z
      - .offset:         258
        .size:           2
        .value_kind:     hidden_remainder_x
      - .offset:         260
        .size:           2
        .value_kind:     hidden_remainder_y
      - .offset:         262
        .size:           2
        .value_kind:     hidden_remainder_z
      - .offset:         280
        .size:           8
        .value_kind:     hidden_global_offset_x
      - .offset:         288
        .size:           8
        .value_kind:     hidden_global_offset_y
      - .offset:         296
        .size:           8
        .value_kind:     hidden_global_offset_z
      - .offset:         304
        .size:           2
        .value_kind:     hidden_grid_dims
      - .offset:         328
        .size:           8
        .value_kind:     hidden_multigrid_sync_arg
      - .offset:         360
        .size:           4
        .value_kind:     hidden_dynamic_lds_size
    .group_segment_fixed_size: 0
    .kernarg_segment_align: 8
    .kernarg_segment_size: 496
    .language:       OpenCL C
    .language_version:
      - 2
      - 0
    .max_flat_workgroup_size: 512
    .name:           _Z11mega_kernel6Params
    .private_segment_fixed_size: 0
    .sgpr_count:     108
    .sgpr_spill_count: 212
    .symbol:         _Z11mega_kernel6Params.kd
    .uniform_work_group_size: 1
    .uses_dynamic_stack: false
    .vgpr_count:     254
    .vgpr_spill_count: 0
    .wavefront_size: 64
